# v18 + attention queue: next ticket atomic and counter snapshot issued at the last key tile of the running unit (pop round trip under the unit tail)
# speedup vs baseline: 1.0020x; 1.0020x over previous
.LBB0_151:
	v_readlane_b32 s0, v252, 0
	s_mov_b32 s78, s0
	v_readlane_b32 s0, v254, 5
	s_ashr_i32 s2, s0, 2
	s_and_b32 s3, s0, 3
	s_lshl_b32 s0, s2, 6
	s_ashr_i32 s1, s0, 31
	v_writelane_b32 v254, s0, 8
	s_lshl_b32 s79, s2, 5
	s_lshl_b32 s4, s2, 9
	v_writelane_b32 v254, s1, 9
	s_mov_b32 s0, s2
	v_writelane_b32 v254, s0, 10
	s_mov_b64 s[10:11], -1
	s_mov_b64 s[12:13], 0
	v_writelane_b32 v254, s1, 11
	s_lshl_b32 s0, s2, 4
	v_writelane_b32 v254, s0, 12
	v_writelane_b32 v254, s73, 13
	v_writelane_b32 v254, s80, 14
	s_cmp_lt_i32 s3, 2
	s_mov_b64 s[8:9], 0
	v_writelane_b32 v254, s81, 15
	s_cbranch_scc1 .LBB0_359
	s_cmp_eq_u32 s3, 2
	s_mov_b64 s[8:9], -1
	s_cbranch_scc0 .LBB0_358
	v_writelane_b32 v254, s3, 16
	v_cmp_eq_u32_e64 s[42:43], 0, v218
	v_readlane_b32 s0, v254, 8
	v_readlane_b32 s1, v254, 9
	s_lshl_b64 s[2:3], s[0:1], 2
	v_readlane_b32 s0, v252, 13
	s_add_u32 s2, s0, s2
	v_readlane_b32 s0, v252, 14
	s_addc_u32 s3, s0, s3
	v_writelane_b32 v254, s2, 17
	s_nop 1
	v_writelane_b32 v254, s3, 18
	s_nop 0
	v_readlane_b32 s0, v254, 10
	v_readlane_b32 s1, v254, 11
	s_lshl_b32 s0, s0, 3
	s_ashr_i32 s1, s0, 31
	v_writelane_b32 v254, s0, 19
	s_nop 1
	v_writelane_b32 v254, s1, 20
	s_add_u32 s0, s88, 0x4800000
	v_writelane_b32 v254, s0, 21
	s_addc_u32 s0, s89, 0
	v_writelane_b32 v254, s0, 23
	s_add_u32 s0, s88, 0x4e00000
	v_writelane_b32 v254, s0, 24
	s_addc_u32 s0, s89, 0
	v_writelane_b32 v254, s0, 25
	s_add_u32 s0, s88, 0x5000000
	v_writelane_b32 v254, s0, 26
	s_addc_u32 s0, s89, 0
	v_writelane_b32 v254, s0, 27
	s_add_u32 s0, s88, 0x6900000
	v_writelane_b32 v254, s0, 28
	s_addc_u32 s0, s89, 0
	v_writelane_b32 v254, s0, 30
	s_add_u32 s0, s88, 0x8200000
	v_writelane_b32 v254, s0, 31
	s_addc_u32 s0, s89, 0
	v_writelane_b32 v254, s0, 33
	s_add_u32 s0, s88, 0x8e00000
	v_writelane_b32 v254, s0, 34
	s_addc_u32 s0, s89, 0
	v_writelane_b32 v254, s0, 36
	s_add_u32 s0, s88, 0x5800000
	v_writelane_b32 v254, s0, 37
	s_addc_u32 s0, s89, 0
	v_writelane_b32 v254, s0, 39
	s_add_u32 s0, s88, 0xa00000
	v_writelane_b32 v254, s0, 41
	s_addc_u32 s0, s89, 0
	v_writelane_b32 v254, s0, 43
	s_add_u32 s0, s88, 0x400000
	v_writelane_b32 v254, s0, 44
	s_addc_u32 s0, s89, 0
	v_writelane_b32 v254, s0, 46
	s_add_u32 s0, s88, 0x600000
	v_writelane_b32 v254, s0, 48
	s_addc_u32 s0, s89, 0
	v_writelane_b32 v254, s0, 50
	s_add_u32 s0, s88, 0x3c00000
	v_writelane_b32 v254, s0, 52
	s_addc_u32 s0, s89, 0
	v_writelane_b32 v254, s0, 53
	s_add_u32 s0, s88, 0x4000000
	v_writelane_b32 v254, s0, 54
	s_addc_u32 s0, s89, 0
	v_writelane_b32 v254, s0, 56
	s_add_u32 s0, s88, 0x4400000
	v_writelane_b32 v254, s0, 57
	s_addc_u32 s0, s89, 0
	s_cmp_eq_u32 s73, 0
	v_writelane_b32 v254, s0, 58
	s_cselect_b64 s[12:13], -1, 0
	s_add_u32 s0, s88, 0x8000
	v_writelane_b32 v254, s0, 59
	s_addc_u32 s0, s89, 0
	s_add_u32 s14, s88, 0x4200
	v_writelane_b32 v254, s0, 60
	s_addc_u32 s15, s89, 0
	s_and_b32 s0, s73, 3
	s_ashr_i32 s2, s73, 2
	s_lshl_b32 s1, s2, 5
	s_lshl_b32 s2, s2, 12
	s_lshl_b32 s3, s0, 10
	s_or_b32 s80, s2, s3
	s_lshl_b32 s51, s73, 5
	s_lshl_b32 s5, s0, 12
	s_addk_i32 s80, 0x3000
	s_lshl_b32 s16, s73, 10
	s_lshl_b32 s10, s73, 3
	s_and_b32 s6, s51, 32
	s_add_i32 s7, s5, s1
	s_add_i32 s17, s16, 0
	s_add_i32 s38, s80, 0
	s_bfe_u32 s2, s73, 0x10001
	s_cmp_eq_u32 s2, 0
	s_cselect_b64 s[8:9], -1, 0
	v_writelane_b32 v254, s8, 61
	s_add_u32 s5, s88, 0xa200
	s_mov_b32 s81, s1
	v_writelane_b32 v254, s9, 62
	v_writelane_b32 v254, s5, 63
	s_addc_u32 s5, s89, 0
	s_cmp_lt_i32 s73, 4
	v_writelane_b32 v255, s5, 0
	s_cselect_b64 s[8:9], -1, 0
	v_writelane_b32 v255, s8, 2
	s_lshl_b32 s2, s2, 16
	v_readlane_b32 s5, v252, 15
	v_writelane_b32 v255, s9, 3
	s_add_u32 s2, s5, s2
	v_readlane_b32 s5, v252, 16
	s_addc_u32 s5, s5, 0
	v_writelane_b32 v255, s6, 4
	s_lshl_b32 s6, s6, 8
	s_add_u32 s2, s2, s6
	v_writelane_b32 v255, s2, 6
	s_addc_u32 s2, s5, 0
	v_writelane_b32 v255, s2, 7
	s_add_u32 s2, s88, 0x300000
	v_writelane_b32 v255, s2, 8
	s_addc_u32 s2, s89, 0
	s_add_u32 s39, s88, 0x1800
	s_addc_u32 s8, s89, 0
	v_writelane_b32 v255, s2, 9
	s_add_u32 s2, s88, 0x9000
	v_writelane_b32 v255, s2, 10
	s_addc_u32 s2, s89, 0
	v_writelane_b32 v255, s2, 11
	s_lshl_b32 s2, s73, 9
	s_add_i32 s2, s2, 0
	s_add_i32 s2, s2, 0x21800
	v_writelane_b32 v255, s2, 12
	s_add_u32 s18, s88, 0x5900000
	s_mul_i32 s2, s73, 0x2200
	s_addc_u32 s19, s89, 0
	s_add_i32 s9, s2, 0
	s_add_u32 s26, s88, 0x7200000
	s_addc_u32 s27, s89, 0
	s_lshl_b32 s2, s0, 11
	v_writelane_b32 v255, s7, 13
	s_sub_i32 s5, s7, s2
	v_writelane_b32 v255, s5, 14
	s_lshl_b32 s5, s73, 7
	s_add_i32 s6, s5, 0
	s_add_i32 s6, s6, 0x22800
	s_add_u32 s5, s88, 0x9800
	v_writelane_b32 v255, s5, 15
	s_addc_u32 s5, s89, 0
	v_writelane_b32 v255, s5, 16
	s_add_u32 s5, s88, 0x8800
	v_writelane_b32 v255, s5, 17
	s_addc_u32 s5, s89, 0
	v_writelane_b32 v255, s5, 18
	s_lshl_b32 s5, s0, 4
	s_add_i32 s3, s3, 0
	v_writelane_b32 v255, s5, 19
	s_add_i32 s7, s3, 0x2000
	v_writelane_b32 v255, s3, 20
	s_add_u32 s3, s88, 0x4410000
	v_writelane_b32 v255, s3, 22
	s_addc_u32 s3, s89, 0
	v_writelane_b32 v255, s3, 23
	s_add_u32 s3, s88, 0x4010000
	v_writelane_b32 v255, s3, 24
	s_addc_u32 s3, s89, 0
	v_writelane_b32 v255, s3, 25
	s_lshl_b32 s3, s73, 11
	v_writelane_b32 v255, s3, 26
	s_add_i32 s2, s2, s1
	v_writelane_b32 v255, s2, 27
	s_lshl_b32 s2, s0, 9
	s_mulk_i32 s0, 0x3000
	v_writelane_b32 v255, s2, 29
	s_add_i32 s0, s0, s1
	v_writelane_b32 v255, s0, 30
	v_and_b32_e32 v174, 31, v205
	v_add_u32_e32 v174, s79, v174
	v_lshlrev_b32_e32 v174, 4, v174
	v_lshrrev_b32_e32 v175, 5, v205
	v_lshl_add_u32 v174, v175, 12, v174
	v_mov_b32_e32 v175, 0
	v_readlane_b32 s100, v254, 59
	v_readlane_b32 s101, v254, 60
	s_nop 1
	v_lshl_add_u64 v[174:175], s[100:101], 0, v[174:175]
	v_readlane_b32 s100, v254, 17
	v_readlane_b32 s101, v254, 18
	s_nop 3
	v_mov_b32_e32 v182, s100
	v_mov_b32_e32 v183, s101
	s_mov_b64 s[100:101], exec
	s_mov_b64 exec, s[12:13]
	global_load_dword v184, v[174:175], off sc1
	s_mov_b64 exec, s[42:43]
	global_atomic_add v221, v[182:183], v181, off sc0
	s_mov_b64 exec, s[100:101]
	s_branch .LBB0_156

.LBB0_156:
	s_waitcnt lgkmcnt(0)
	s_barrier
	s_andn2_b64 vcc, exec, s[12:13]
	s_cbranch_vccnz .Lahead_none
	s_waitcnt vmcnt(0)
	v_mov_b32_e32 v178, v184
.Lahead_none:
	s_and_saveexec_b64 s[28:29], s[42:43]
	s_cbranch_execz .LBB0_160
	s_mov_b64 s[40:41], exec
	v_readlane_b32 s0, v253, 61
	v_mov_b32_e32 v0, v221
	s_nop 1
	v_mov_b32_e32 v1, s0
	ds_write_b32 v1, v0

.LBB0_203:
	v_add_u32_e32 v56, 0, v112
	s_waitcnt vmcnt(0)
	s_mov_b64 s[100:101], exec
	s_mov_b64 exec, s[12:13]
	global_load_dword v184, v[174:175], off sc1
	s_mov_b64 exec, s[42:43]
	global_atomic_add v221, v[182:183], v181, off sc0
	s_mov_b64 exec, s[100:101]
	s_barrier
	v_add_u32_e32 v36, v56, v113
	ds_read_b128 v[32:35], v36 offset:4096
	ds_read_b128 v[48:51], v36
	v_add_u32_e32 v57, v56, v114
	ds_read_b128 v[52:55], v57 offset:4096
	ds_read_b128 v[94:97], v57
	v_add_u32_e32 v58, v56, v111
	s_waitcnt lgkmcnt(3)
	v_mfma_f32_32x32x16_bf16 v[32:47], v[32:35], v[76:79], 0
	v_add_u32_e32 v56, v56, v110
	v_readlane_b32 s0, v255, 2
	v_readlane_b32 s1, v255, 3
	s_andn2_b64 vcc, exec, s[0:1]
	ds_read_b128 v[100:103], v58
	s_waitcnt lgkmcnt(2)
	v_mfma_f32_32x32x16_bf16 v[32:47], v[52:55], v[72:75], v[32:47]
	ds_read_b128 v[52:55], v58 offset:4096
	s_waitcnt lgkmcnt(0)
	v_mfma_f32_32x32x16_bf16 v[32:47], v[52:55], v[68:71], v[32:47]
	ds_read_b128 v[52:55], v56 offset:4096
	ds_read_b128 v[110:113], v56
	s_waitcnt lgkmcnt(1)
	v_mfma_f32_32x32x16_bf16 v[32:47], v[52:55], v[64:67], v[32:47]
	v_add_u32_e32 v52, 0, v108
	v_add3_u32 v106, v52, v109, v106
	ds_read_b64_tr_b16 v[90:91], v106 offset:12288
	ds_read_b64_tr_b16 v[92:93], v106 offset:12800
	ds_read_b64_tr_b16 v[82:83], v106 offset:13312
	ds_read_b64_tr_b16 v[84:85], v106 offset:13824
	v_mfma_f32_32x32x16_bf16 v[48:63], v[48:51], v[76:79], 0
	v_add_u32_e32 v76, 0xc0, v107
	v_cvt_f32_i32_e32 v107, v76
	ds_read_b64_tr_b16 v[86:87], v106 offset:14336
	ds_read_b64_tr_b16 v[88:89], v106 offset:14848
	ds_read_b64_tr_b16 v[76:77], v106 offset:15360
	ds_read_b64_tr_b16 v[78:79], v106 offset:15872
	v_mfma_f32_32x32x16_bf16 v[48:63], v[94:97], v[72:75], v[48:63]
	v_add_f32_e32 v74, 0x41d00000, v107
	v_add_f32_e32 v75, 0x41d80000, v107
	v_add_f32_e32 v72, 0x42000000, v74
	v_add_f32_e32 v73, 0x42000000, v75
	v_fma_f32 v72, v72, v104, v105
	v_fma_f32 v73, v73, v104, v105
	v_exp_f32_e32 v72, v72
	v_mfma_f32_32x32x16_bf16 v[48:63], v[100:103], v[68:71], v[48:63]
	v_exp_f32_e32 v73, v73
	s_nop 0
	v_pk_mul_f32 v[68:69], v[46:47], v[72:73]
	v_fma_f32 v46, v74, v104, v105
	v_fma_f32 v47, v75, v104, v105
	s_waitcnt lgkmcnt(8)
	v_mfma_f32_32x32x16_bf16 v[48:63], v[110:113], v[64:67], v[48:63]
	v_exp_f32_e32 v46, v46
	v_exp_f32_e32 v47, v47
	v_add_f32_e32 v65, 0x41c80000, v107
	v_add_f32_e32 v67, 0x41980000, v107
	v_add_f32_e32 v74, 0x41200000, v107
	v_add_f32_e32 v75, 0x41300000, v107
	v_add_f32_e32 v72, 0x42000000, v74
	s_nop 4
	v_pk_mul_f32 v[62:63], v[62:63], v[46:47]
	v_add_f32_e32 v46, 0x41c00000, v107
	v_add_f32_e32 v47, 0x42000000, v46
	v_fma_f32 v47, v47, v104, v105
	v_exp_f32_e32 v64, v47
	v_fma_f32 v46, v46, v104, v105
	v_fma_f32 v47, v65, v104, v105
	v_exp_f32_e32 v46, v46
	v_exp_f32_e32 v47, v47
	v_add_f32_e32 v73, 0x42000000, v75
	v_fma_f32 v74, v74, v104, v105
	v_fma_f32 v75, v75, v104, v105
	v_pk_mul_f32 v[60:61], v[60:61], v[46:47]
	v_add_f32_e32 v46, 0x41900000, v107
	v_add_f32_e32 v47, 0x42000000, v46
	v_fma_f32 v47, v47, v104, v105
	v_exp_f32_e32 v66, v47
	v_fma_f32 v46, v46, v104, v105
	v_fma_f32 v47, v67, v104, v105
	v_exp_f32_e32 v46, v46
	v_exp_f32_e32 v47, v47
	v_exp_f32_e32 v74, v74
	v_exp_f32_e32 v75, v75
	v_fma_f32 v72, v72, v104, v105
	v_pk_mul_f32 v[58:59], v[58:59], v[46:47]
	v_add_f32_e32 v46, 0x41800000, v107
	v_add_f32_e32 v47, 0x42000000, v46
	v_fma_f32 v47, v47, v104, v105
	v_exp_f32_e32 v70, v47
	v_add_f32_e32 v47, 0x41880000, v107
	v_add_f32_e32 v71, 0x42000000, v47
	v_fma_f32 v46, v46, v104, v105
	v_fma_f32 v47, v47, v104, v105
	v_exp_f32_e32 v46, v46
	v_exp_f32_e32 v47, v47
	v_pk_mul_f32 v[54:55], v[54:55], v[74:75]
	v_add_f32_e32 v74, 2.0, v107
	v_fma_f32 v73, v73, v104, v105
	v_add_f32_e32 v75, 0x42000000, v74
	v_exp_f32_e32 v72, v72
	v_exp_f32_e32 v73, v73
	v_fma_f32 v96, v75, v104, v105
	v_add_f32_e32 v75, 0x40400000, v107
	v_pk_mul_f32 v[56:57], v[56:57], v[46:47]
	v_add_f32_e32 v46, 0x41000000, v107
	v_add_f32_e32 v94, 0x42000000, v75
	v_add_f32_e32 v47, 0x42000000, v46
	v_fma_f32 v97, v94, v104, v105
	v_add_f32_e32 v94, 0, v107
	v_fma_f32 v47, v47, v104, v105
	v_add_f32_e32 v95, 0x42000000, v94
	v_pk_mul_f32 v[38:39], v[38:39], v[72:73]
	v_exp_f32_e32 v72, v47
	v_add_f32_e32 v47, 0x41100000, v107
	v_fma_f32 v100, v95, v104, v105
	v_add_f32_e32 v95, 1.0, v107
	v_add_f32_e32 v65, 0x42000000, v65
	v_add_f32_e32 v67, 0x42000000, v67
	v_add_f32_e32 v73, 0x42000000, v47
	v_add_f32_e32 v101, 0x42000000, v95
	v_fma_f32 v65, v65, v104, v105
	v_fma_f32 v67, v67, v104, v105
	v_fma_f32 v71, v71, v104, v105
	v_fma_f32 v73, v73, v104, v105
	v_fma_f32 v46, v46, v104, v105
	v_fma_f32 v47, v47, v104, v105
	v_fma_f32 v74, v74, v104, v105
	v_fma_f32 v75, v75, v104, v105
	v_fma_f32 v101, v101, v104, v105
	v_fma_f32 v94, v94, v104, v105
	v_fmac_f32_e32 v105, v95, v104
	v_exp_f32_e32 v46, v46
	v_exp_f32_e32 v47, v47
	v_exp_f32_e32 v94, v94
	v_exp_f32_e32 v95, v105
	v_exp_f32_e32 v74, v74
	v_exp_f32_e32 v75, v75
	v_exp_f32_e32 v73, v73
	v_pk_mul_f32 v[52:53], v[52:53], v[46:47]
	v_exp_f32_e32 v96, v96
	v_pk_mul_f32 v[46:47], v[48:49], v[94:95]
	v_cvt_pk_bf16_f32 v49, v54, v55
	v_exp_f32_e32 v97, v97
	v_exp_f32_e32 v54, v100
	v_exp_f32_e32 v55, v101
	v_exp_f32_e32 v67, v67
	v_exp_f32_e32 v71, v71
	v_pk_mul_f32 v[50:51], v[50:51], v[74:75]
	v_cvt_pk_bf16_f32 v46, v46, v47
	v_cvt_pk_bf16_f32 v47, v50, v51
	v_cvt_pk_bf16_f32 v48, v52, v53
	v_pk_mul_f32 v[36:37], v[36:37], v[72:73]
	v_pk_mul_f32 v[34:35], v[34:35], v[96:97]
	v_pk_mul_f32 v[32:33], v[32:33], v[54:55]
	v_pk_mul_f32 v[42:43], v[42:43], v[66:67]
	v_cvt_pk_bf16_f32 v32, v32, v33
	v_cvt_pk_bf16_f32 v33, v34, v35
	v_cvt_pk_bf16_f32 v34, v36, v37
	v_pk_mul_f32 v[36:37], v[40:41], v[70:71]
	v_cvt_pk_bf16_f32 v50, v56, v57
	v_cvt_pk_bf16_f32 v36, v36, v37
	v_cvt_pk_bf16_f32 v37, v42, v43
	ds_read_b64_tr_b16 v[40:41], v106 offset:16384
	ds_read_b64_tr_b16 v[42:43], v106 offset:16896
	ds_read_b64_tr_b16 v[54:55], v106 offset:17408
	ds_read_b64_tr_b16 v[56:57], v106 offset:17920
	s_waitcnt lgkmcnt(10)
	v_mfma_f32_32x32x16_bf16 v[16:31], v[46:49], v[90:93], v[16:31]
	v_cvt_pk_bf16_f32 v51, v58, v59
	v_cvt_pk_bf16_f32 v52, v60, v61
	v_cvt_pk_bf16_f32 v53, v62, v63
	v_exp_f32_e32 v65, v65
	v_cvt_pk_bf16_f32 v35, v38, v39
	v_pk_mul_f32 v[38:39], v[44:45], v[64:65]
	s_waitcnt lgkmcnt(2)
	v_mfma_f32_32x32x16_bf16 v[0:15], v[46:49], v[40:43], v[0:15]
	ds_read_b64_tr_b16 v[40:41], v106 offset:18432
	ds_read_b64_tr_b16 v[42:43], v106 offset:18944
	ds_read_b64_tr_b16 v[44:45], v106 offset:19456
	ds_read_b64_tr_b16 v[46:47], v106 offset:19968
	v_cvt_pk_bf16_f32 v38, v38, v39
	v_cvt_pk_bf16_f32 v39, v68, v69
	v_mfma_f32_32x32x16_bf16 v[16:31], v[50:53], v[82:85], v[16:31]
	s_waitcnt lgkmcnt(4)
	v_mfma_f32_32x32x16_bf16 v[0:15], v[50:53], v[54:57], v[0:15]
	v_mfma_f32_32x32x16_bf16 v[16:31], v[32:35], v[86:89], v[16:31]
	s_waitcnt lgkmcnt(2)
	v_mfma_f32_32x32x16_bf16 v[0:15], v[32:35], v[40:43], v[0:15]
	v_mfma_f32_32x32x16_bf16 v[16:31], v[36:39], v[76:79], v[16:31]
	s_waitcnt lgkmcnt(0)
	v_mfma_f32_32x32x16_bf16 v[0:15], v[36:39], v[44:47], v[0:15]
	s_cbranch_vccnz .LBB0_205
	s_lshl_b32 s0, s2, 3
	s_or_b32 s36, s0, s3
	s_ashr_i32 s37, s36, 31
	s_lshl_b64 s[36:37], s[36:37], 14
	v_readlane_b32 s0, v255, 6
	s_add_u32 s36, s0, s36
	v_readlane_b32 s0, v255, 7
	v_lshlrev_b32_e32 v32, 2, v80
	s_addc_u32 s37, s0, s37
	v_ashrrev_i32_e32 v99, 31, v98
	v_ashrrev_i32_e32 v33, 31, v32
	v_or_b32_e32 v38, 1, v32
	v_lshl_add_u64 v[34:35], v[98:99], 2, s[36:37]
	v_lshlrev_b64 v[36:37], 8, v[32:33]
	v_ashrrev_i32_e32 v39, 31, v38
	v_lshl_add_u64 v[36:37], v[34:35], 0, v[36:37]
	v_lshlrev_b64 v[38:39], 8, v[38:39]
	global_store_dword v[36:37], v16, off
	v_lshl_add_u64 v[38:39], v[34:35], 0, v[38:39]
	v_or_b32_e32 v16, 2, v32
	global_store_dword v[38:39], v17, off
	v_ashrrev_i32_e32 v17, 31, v16
	v_or_b32_e32 v40, 3, v32
	v_lshlrev_b64 v[16:17], 8, v[16:17]
	v_ashrrev_i32_e32 v41, 31, v40
	v_lshl_add_u64 v[16:17], v[34:35], 0, v[16:17]
	v_lshlrev_b64 v[40:41], 8, v[40:41]
	global_store_dword v[16:17], v18, off
	v_lshl_add_u64 v[40:41], v[34:35], 0, v[40:41]
	v_add_u32_e32 v18, 8, v32
	global_store_dword v[40:41], v19, off
	v_ashrrev_i32_e32 v19, 31, v18
	v_add_u32_e32 v42, 9, v32
	v_lshlrev_b64 v[18:19], 8, v[18:19]
	v_ashrrev_i32_e32 v43, 31, v42
	v_lshl_add_u64 v[18:19], v[34:35], 0, v[18:19]
	v_lshlrev_b64 v[42:43], 8, v[42:43]
	global_store_dword v[18:19], v20, off
	v_lshl_add_u64 v[42:43], v[34:35], 0, v[42:43]
	v_add_u32_e32 v20, 10, v32
	global_store_dword v[42:43], v21, off
	v_ashrrev_i32_e32 v21, 31, v20
	v_add_u32_e32 v44, 11, v32
	v_lshlrev_b64 v[20:21], 8, v[20:21]
	v_ashrrev_i32_e32 v45, 31, v44
	v_lshl_add_u64 v[20:21], v[34:35], 0, v[20:21]
	v_lshlrev_b64 v[44:45], 8, v[44:45]
	global_store_dword v[20:21], v22, off
	v_lshl_add_u64 v[44:45], v[34:35], 0, v[44:45]
	v_add_u32_e32 v22, 16, v32
	global_store_dword v[44:45], v23, off
	v_ashrrev_i32_e32 v23, 31, v22
	v_add_u32_e32 v46, 17, v32
	v_lshlrev_b64 v[22:23], 8, v[22:23]
	v_ashrrev_i32_e32 v47, 31, v46
	v_lshl_add_u64 v[22:23], v[34:35], 0, v[22:23]
	v_lshlrev_b64 v[46:47], 8, v[46:47]
	global_store_dword v[22:23], v24, off
	v_lshl_add_u64 v[46:47], v[34:35], 0, v[46:47]
	v_add_u32_e32 v24, 18, v32
	global_store_dword v[46:47], v25, off
	v_ashrrev_i32_e32 v25, 31, v24
	v_add_u32_e32 v48, 19, v32
	v_lshlrev_b64 v[24:25], 8, v[24:25]
	v_ashrrev_i32_e32 v49, 31, v48
	v_lshl_add_u64 v[24:25], v[34:35], 0, v[24:25]
	v_lshlrev_b64 v[48:49], 8, v[48:49]
	global_store_dword v[24:25], v26, off
	v_lshl_add_u64 v[48:49], v[34:35], 0, v[48:49]
	v_add_u32_e32 v26, 24, v32
	global_store_dword v[48:49], v27, off
	v_ashrrev_i32_e32 v27, 31, v26
	v_add_u32_e32 v50, 25, v32
	v_lshlrev_b64 v[26:27], 8, v[26:27]
	v_ashrrev_i32_e32 v51, 31, v50
	v_lshl_add_u64 v[26:27], v[34:35], 0, v[26:27]
	v_lshlrev_b64 v[50:51], 8, v[50:51]
	global_store_dword v[26:27], v28, off
	v_lshl_add_u64 v[50:51], v[34:35], 0, v[50:51]
	v_add_u32_e32 v28, 26, v32
	v_add_u32_e32 v32, 27, v32
	global_store_dword v[50:51], v29, off
	v_ashrrev_i32_e32 v29, 31, v28
	v_ashrrev_i32_e32 v33, 31, v32
	v_lshlrev_b64 v[28:29], 8, v[28:29]
	v_lshlrev_b64 v[32:33], 8, v[32:33]
	v_lshl_add_u64 v[28:29], v[34:35], 0, v[28:29]
	v_lshl_add_u64 v[32:33], v[34:35], 0, v[32:33]
	global_store_dword v[28:29], v30, off
	global_store_dword v[32:33], v31, off
	global_store_dword v[36:37], v0, off offset:128
	global_store_dword v[38:39], v1, off offset:128
	global_store_dword v[16:17], v2, off offset:128
	global_store_dword v[40:41], v3, off offset:128
	global_store_dword v[18:19], v4, off offset:128
	global_store_dword v[42:43], v5, off offset:128
	global_store_dword v[20:21], v6, off offset:128
	global_store_dword v[44:45], v7, off offset:128
	global_store_dword v[22:23], v8, off offset:128
	global_store_dword v[46:47], v9, off offset:128
	global_store_dword v[24:25], v10, off offset:128
	global_store_dword v[48:49], v11, off offset:128
	global_store_dword v[26:27], v12, off offset:128
	global_store_dword v[50:51], v13, off offset:128
	global_store_dword v[28:29], v14, off offset:128
	global_store_dword v[32:33], v15, off offset:128

.LBB0_242:
	s_mul_i32 s37, s60, 0x5000
	s_add_i32 s37, s37, 0
	v_add_u32_e32 v36, s37, v144
	s_waitcnt vmcnt(0)
	s_mov_b64 s[100:101], exec
	s_mov_b64 exec, s[12:13]
	global_load_dword v184, v[174:175], off sc1
	s_mov_b64 exec, s[42:43]
	global_atomic_add v221, v[182:183], v181, off sc0
	s_mov_b64 exec, s[100:101]
	s_barrier
	v_add_u32_e32 v32, v36, v151
	ds_read_b128 v[48:51], v32
	ds_read_b128 v[32:35], v32 offset:4096
	v_add_u32_e32 v37, v36, v145
	ds_read_b128 v[64:67], v37
	ds_read_b128 v[52:55], v37 offset:4096
	v_add_u32_e32 v37, v36, v146
	v_add_u32_e32 v36, v36, v147
	ds_read_b128 v[68:71], v37
	ds_read_b128 v[56:59], v37 offset:4096
	ds_read_b128 v[72:75], v36
	ds_read_b128 v[60:63], v36 offset:4096
	s_waitcnt lgkmcnt(6)
	v_mfma_f32_32x32x16_bf16 v[32:47], v[32:35], v[94:97], 0
	s_lshl_b32 s0, s54, 6
	v_add_u32_e32 v130, s33, v116
	s_mov_b32 s1, 0x800000
	s_mov_b32 s72, 0x40c00000
	s_mov_b64 s[66:67], 0x4000
	v_readlane_b32 s73, v254, 13
	s_waitcnt lgkmcnt(4)
	v_mfma_f32_32x32x16_bf16 v[32:47], v[52:55], v[90:93], v[32:47]
	v_add3_u32 v52, s37, v117, v143
	v_add_u32_e32 v131, v52, v142
	ds_read_b64_tr_b16 v[110:111], v131 offset:12288
	ds_read_b64_tr_b16 v[112:113], v131 offset:12800
	ds_read_b64_tr_b16 v[106:107], v131 offset:13312
	ds_read_b64_tr_b16 v[108:109], v131 offset:13824
	ds_read_b64_tr_b16 v[102:103], v131 offset:14336
	ds_read_b64_tr_b16 v[104:105], v131 offset:14848
	ds_read_b64_tr_b16 v[98:99], v131 offset:15360
	ds_read_b64_tr_b16 v[100:101], v131 offset:15872
	s_add_i32 s37, s0, 0xffffff80
	s_addk_i32 s0, 0xffbf
	s_cmp_ge_u32 s0, s33
	s_cselect_b64 s[58:59], -1, 0
	s_waitcnt lgkmcnt(10)
	v_mfma_f32_32x32x16_bf16 v[32:47], v[56:59], v[86:89], v[32:47]
	s_cmp_lt_u32 s0, s33
	s_cselect_b64 s[54:55], -1, 0
	s_cmp_gt_u32 s37, s50
	s_cselect_b64 s[62:63], -1, 0
	s_or_b64 s[54:55], s[54:55], s[62:63]
	s_mov_b64 s[62:63], -1
	s_and_b64 vcc, exec, s[54:55]
	s_waitcnt lgkmcnt(8)
	v_mfma_f32_32x32x16_bf16 v[32:47], v[60:63], v[82:85], v[32:47]
	v_mfma_f32_32x32x16_bf16 v[48:63], v[48:51], v[94:97], 0
	v_mfma_f32_32x32x16_bf16 v[48:63], v[64:67], v[90:93], v[48:63]
	v_mfma_f32_32x32x16_bf16 v[48:63], v[68:71], v[86:89], v[48:63]
	v_mfma_f32_32x32x16_bf16 v[48:63], v[72:75], v[82:85], v[48:63]
	s_cbranch_vccnz .LBB0_244
	v_add_u32_e32 v64, s37, v141
	v_sub_u32_e32 v64, v130, v64
	v_cvt_f32_i32_e32 v64, v64
	s_mov_b32 s0, 0xc2000000
	v_cmp_lt_f32_e32 vcc, 0, v64
	v_add_f32_e32 v65, -1.0, v64
	s_mov_b32 s54, -2.0
	v_cndmask_b32_e32 v66, v137, v115, vcc
	v_mul_f32_e64 v66, |v64|, v66
	v_cmp_lt_f32_e32 vcc, 0, v65
	v_exp_f32_e32 v133, v66
	s_mov_b32 s55, 0xc0400000
	v_cndmask_b32_e32 v66, v137, v115, vcc
	v_mul_f32_e64 v66, |v65|, v66
	v_exp_f32_e32 v134, v66
	v_pk_add_f32 v[66:67], v[64:65], s[0:1] op_sel_hi:[1,0]
	s_mov_b64 s[62:63], 0
	v_cmp_lt_f32_e32 vcc, 0, v66
	s_nop 1
	v_cndmask_b32_e32 v68, v137, v115, vcc
	v_cmp_lt_f32_e32 vcc, 0, v67
	v_mul_f32_e64 v68, |v66|, v68
	v_exp_f32_e32 v68, v68
	v_cndmask_b32_e32 v69, v137, v115, vcc
	v_mul_f32_e64 v69, |v67|, v69
	v_exp_f32_e32 v69, v69
	v_cmp_neq_f32_e32 vcc, 0, v67
	s_nop 1
	v_cndmask_b32_e32 v67, 2.0, v69, vcc
	v_cmp_neq_f32_e32 vcc, 0, v66
	s_nop 1
	v_cndmask_b32_e32 v66, 2.0, v68, vcc
	v_pk_mul_f32 v[116:117], v[32:33], v[66:67]
	v_pk_add_f32 v[66:67], v[64:65], s[54:55] op_sel_hi:[0,1]
	v_cmp_lt_f32_e32 vcc, 0, v66
	s_mov_b32 s54, 0xc1000000
	s_mov_b32 s55, 0xc1100000
	v_cndmask_b32_e32 v68, v137, v115, vcc
	v_mul_f32_e64 v68, |v66|, v68
	v_cmp_lt_f32_e32 vcc, 0, v67
	v_exp_f32_e32 v135, v68
	s_nop 0
	v_cndmask_b32_e32 v68, v137, v115, vcc
	v_mul_f32_e64 v68, |v67|, v68
	v_exp_f32_e32 v141, v68
	v_pk_add_f32 v[68:69], v[66:67], s[0:1] op_sel_hi:[1,0]
	s_nop 0
	v_cmp_lt_f32_e32 vcc, 0, v68
	s_nop 1
	v_cndmask_b32_e32 v70, v137, v115, vcc
	v_cmp_lt_f32_e32 vcc, 0, v69
	v_mul_f32_e64 v70, |v68|, v70
	v_exp_f32_e32 v70, v70
	v_cndmask_b32_e32 v71, v137, v115, vcc
	v_mul_f32_e64 v71, |v69|, v71
	v_exp_f32_e32 v71, v71
	v_cmp_neq_f32_e32 vcc, 0, v69
	s_nop 1
	v_cndmask_b32_e32 v69, 2.0, v71, vcc
	v_cmp_neq_f32_e32 vcc, 0, v68
	s_nop 1
	v_cndmask_b32_e32 v68, 2.0, v70, vcc
	v_pk_mul_f32 v[118:119], v[34:35], v[68:69]
	v_pk_add_f32 v[68:69], v[64:65], s[54:55] op_sel_hi:[0,1]
	v_cmp_lt_f32_e32 vcc, 0, v68
	s_mov_b32 s54, 0xc1200000
	s_mov_b32 s55, 0xc1300000
	v_cndmask_b32_e32 v70, v137, v115, vcc
	v_mul_f32_e64 v70, |v68|, v70
	v_cmp_lt_f32_e32 vcc, 0, v69
	v_exp_f32_e32 v142, v70
	s_nop 0
	v_cndmask_b32_e32 v70, v137, v115, vcc
	v_mul_f32_e64 v70, |v69|, v70
	v_exp_f32_e32 v143, v70
	v_pk_add_f32 v[70:71], v[68:69], s[0:1] op_sel_hi:[1,0]
	s_nop 0
	v_cmp_lt_f32_e32 vcc, 0, v70
	s_nop 1
	v_cndmask_b32_e32 v72, v137, v115, vcc
	v_cmp_lt_f32_e32 vcc, 0, v71
	v_mul_f32_e64 v72, |v70|, v72
	v_exp_f32_e32 v72, v72
	v_cndmask_b32_e32 v73, v137, v115, vcc
	v_mul_f32_e64 v73, |v71|, v73
	v_exp_f32_e32 v73, v73
	v_cmp_neq_f32_e32 vcc, 0, v71
	s_nop 1
	v_cndmask_b32_e32 v71, 2.0, v73, vcc
	v_cmp_neq_f32_e32 vcc, 0, v70
	s_nop 1
	v_cndmask_b32_e32 v70, 2.0, v72, vcc
	v_pk_mul_f32 v[120:121], v[36:37], v[70:71]
	v_pk_add_f32 v[70:71], v[64:65], s[54:55] op_sel_hi:[0,1]
	v_cmp_lt_f32_e32 vcc, 0, v70
	s_mov_b32 s54, 0xc1800000
	s_mov_b32 s55, 0xc1880000
	v_cndmask_b32_e32 v72, v137, v115, vcc
	v_mul_f32_e64 v72, |v70|, v72
	v_cmp_lt_f32_e32 vcc, 0, v71
	v_exp_f32_e32 v144, v72
	s_nop 0
	v_cndmask_b32_e32 v72, v137, v115, vcc
	v_mul_f32_e64 v72, |v71|, v72
	v_exp_f32_e32 v145, v72
	v_pk_add_f32 v[72:73], v[70:71], s[0:1] op_sel_hi:[1,0]
	s_nop 0
	v_cmp_lt_f32_e32 vcc, 0, v72
	s_nop 1
	v_cndmask_b32_e32 v74, v137, v115, vcc
	v_cmp_lt_f32_e32 vcc, 0, v73
	v_mul_f32_e64 v74, |v72|, v74
	v_exp_f32_e32 v74, v74
	v_cndmask_b32_e32 v75, v137, v115, vcc
	v_mul_f32_e64 v75, |v73|, v75
	v_exp_f32_e32 v75, v75
	v_cmp_neq_f32_e32 vcc, 0, v73
	s_nop 1
	v_cndmask_b32_e32 v73, 2.0, v75, vcc
	v_cmp_neq_f32_e32 vcc, 0, v72
	s_nop 1
	v_cndmask_b32_e32 v72, 2.0, v74, vcc
	v_pk_mul_f32 v[122:123], v[38:39], v[72:73]
	v_pk_add_f32 v[72:73], v[64:65], s[54:55] op_sel_hi:[0,1]
	v_cmp_lt_f32_e32 vcc, 0, v72
	s_mov_b32 s54, 0xc1900000
	s_mov_b32 s55, 0xc1980000
	v_cndmask_b32_e32 v74, v137, v115, vcc
	v_mul_f32_e64 v74, |v72|, v74
	v_cmp_lt_f32_e32 vcc, 0, v73
	v_exp_f32_e32 v146, v74
	s_nop 0
	v_cndmask_b32_e32 v74, v137, v115, vcc
	v_mul_f32_e64 v74, |v73|, v74
	v_exp_f32_e32 v147, v74
	v_pk_add_f32 v[74:75], v[72:73], s[0:1] op_sel_hi:[1,0]
	s_nop 0
	v_cmp_lt_f32_e32 vcc, 0, v74
	s_nop 1
	v_cndmask_b32_e32 v76, v137, v115, vcc
	v_cmp_lt_f32_e32 vcc, 0, v75
	v_mul_f32_e64 v76, |v74|, v76
	v_exp_f32_e32 v76, v76
	v_cndmask_b32_e32 v77, v137, v115, vcc
	v_mul_f32_e64 v77, |v75|, v77
	v_exp_f32_e32 v77, v77
	v_cmp_neq_f32_e32 vcc, 0, v75
	s_nop 1
	v_cndmask_b32_e32 v75, 2.0, v77, vcc
	v_cmp_neq_f32_e32 vcc, 0, v74
	s_nop 1
	v_cndmask_b32_e32 v74, 2.0, v76, vcc
	v_pk_mul_f32 v[124:125], v[40:41], v[74:75]
	v_pk_add_f32 v[74:75], v[64:65], s[54:55] op_sel_hi:[0,1]
	v_cmp_lt_f32_e32 vcc, 0, v74
	s_mov_b32 s54, 0xc1c00000
	s_mov_b32 s55, 0xc1c80000
	v_cndmask_b32_e32 v76, v137, v115, vcc
	v_mul_f32_e64 v76, |v74|, v76
	v_cmp_lt_f32_e32 vcc, 0, v75
	v_exp_f32_e32 v151, v76
	s_nop 0
	v_cndmask_b32_e32 v76, v137, v115, vcc
	v_mul_f32_e64 v76, |v75|, v76
	v_exp_f32_e32 v152, v76
	v_pk_add_f32 v[76:77], v[74:75], s[0:1] op_sel_hi:[1,0]
	s_nop 0
	v_cmp_lt_f32_e32 vcc, 0, v76
	s_nop 1
	v_cndmask_b32_e32 v78, v137, v115, vcc
	v_cmp_lt_f32_e32 vcc, 0, v77
	v_mul_f32_e64 v78, |v76|, v78
	v_exp_f32_e32 v78, v78
	v_cndmask_b32_e32 v79, v137, v115, vcc
	v_mul_f32_e64 v79, |v77|, v79
	v_exp_f32_e32 v79, v79
	v_cmp_neq_f32_e32 vcc, 0, v77
	s_nop 1
	v_cndmask_b32_e32 v77, 2.0, v79, vcc
	v_cmp_neq_f32_e32 vcc, 0, v76
	s_nop 1
	v_cndmask_b32_e32 v76, 2.0, v78, vcc
	v_pk_mul_f32 v[126:127], v[42:43], v[76:77]
	v_pk_add_f32 v[76:77], v[64:65], s[54:55] op_sel_hi:[0,1]
	v_cmp_lt_f32_e32 vcc, 0, v76
	s_mov_b32 s54, 0xc1d00000
	s_mov_b32 s55, 0xc1d80000
	v_cndmask_b32_e32 v78, v137, v115, vcc
	v_mul_f32_e64 v78, |v76|, v78
	v_cmp_lt_f32_e32 vcc, 0, v77
	v_exp_f32_e32 v153, v78
	s_nop 0
	v_cndmask_b32_e32 v78, v137, v115, vcc
	v_mul_f32_e64 v78, |v77|, v78
	v_exp_f32_e32 v154, v78
	v_pk_add_f32 v[78:79], v[76:77], s[0:1] op_sel_hi:[1,0]
	s_nop 0
	v_cmp_lt_f32_e32 vcc, 0, v78
	s_nop 1
	v_cndmask_b32_e32 v128, v137, v115, vcc
	v_cmp_lt_f32_e32 vcc, 0, v79
	v_mul_f32_e64 v128, |v78|, v128
	v_exp_f32_e32 v128, v128
	v_cndmask_b32_e32 v129, v137, v115, vcc
	v_mul_f32_e64 v129, |v79|, v129
	v_exp_f32_e32 v129, v129
	v_cmp_neq_f32_e32 vcc, 0, v79
	s_nop 1
	v_cndmask_b32_e32 v79, 2.0, v129, vcc
	v_cmp_neq_f32_e32 vcc, 0, v78
	s_nop 1
	v_cndmask_b32_e32 v78, 2.0, v128, vcc
	v_pk_mul_f32 v[128:129], v[44:45], v[78:79]
	v_pk_add_f32 v[78:79], v[64:65], s[54:55] op_sel_hi:[0,1]
	v_add_f32_e32 v132, 0xc2000000, v78
	v_cmp_lt_f32_e32 vcc, 0, v78
	s_nop 1
	v_cndmask_b32_e32 v155, v137, v115, vcc
	v_cmp_lt_f32_e32 vcc, 0, v132
	v_mul_f32_e64 v155, |v78|, v155
	v_exp_f32_e32 v155, v155
	v_cndmask_b32_e32 v156, v137, v115, vcc
	v_mul_f32_e64 v156, |v132|, v156
	v_exp_f32_e32 v156, v156
	v_cmp_lt_f32_e32 vcc, 0, v79
	s_nop 1
	v_cndmask_b32_e32 v157, v137, v115, vcc
	v_mul_f32_e64 v157, |v79|, v157
	v_exp_f32_e32 v157, v157
	v_cmp_neq_f32_e32 vcc, 0, v132
	s_nop 1
	v_cndmask_b32_e32 v132, 2.0, v156, vcc
	v_add_f32_e32 v156, 0xc2000000, v79
	v_cmp_lt_f32_e32 vcc, 0, v156
	v_mul_f32_e32 v132, v46, v132
	s_nop 0
	v_cndmask_b32_e32 v158, v137, v115, vcc
	v_cmp_neq_f32_e32 vcc, 0, v79
	v_mul_f32_e64 v158, |v156|, v158
	v_exp_f32_e32 v158, v158
	v_cndmask_b32_e32 v79, 2.0, v157, vcc
	v_cmp_neq_f32_e32 vcc, 0, v78
	s_nop 1
	v_cndmask_b32_e32 v78, 2.0, v155, vcc
	v_cmp_neq_f32_e32 vcc, 0, v77
	s_nop 1
	v_cndmask_b32_e32 v77, 2.0, v154, vcc
	v_cmp_neq_f32_e32 vcc, 0, v76
	s_nop 1
	v_cndmask_b32_e32 v76, 2.0, v153, vcc
	v_cmp_neq_f32_e32 vcc, 0, v75
	s_nop 1
	v_cndmask_b32_e32 v75, 2.0, v152, vcc
	v_cmp_neq_f32_e32 vcc, 0, v74
	s_nop 1
	v_cndmask_b32_e32 v74, 2.0, v151, vcc
	v_cmp_neq_f32_e32 vcc, 0, v73
	s_nop 1
	v_cndmask_b32_e32 v73, 2.0, v147, vcc
	v_cmp_neq_f32_e32 vcc, 0, v72
	s_nop 1
	v_cndmask_b32_e32 v72, 2.0, v146, vcc
	v_cmp_neq_f32_e32 vcc, 0, v71
	s_nop 1
	v_cndmask_b32_e32 v71, 2.0, v145, vcc
	v_cmp_neq_f32_e32 vcc, 0, v70
	s_nop 1
	v_cndmask_b32_e32 v70, 2.0, v144, vcc
	v_cmp_neq_f32_e32 vcc, 0, v69
	s_nop 1
	v_cndmask_b32_e32 v69, 2.0, v143, vcc
	v_cmp_neq_f32_e32 vcc, 0, v68
	s_nop 1
	v_cndmask_b32_e32 v68, 2.0, v142, vcc
	v_cmp_neq_f32_e32 vcc, 0, v67
	s_nop 1
	v_cndmask_b32_e32 v67, 2.0, v141, vcc
	v_cmp_neq_f32_e32 vcc, 0, v66
	s_nop 1
	v_cndmask_b32_e32 v66, 2.0, v135, vcc
	v_cmp_neq_f32_e32 vcc, 0, v64
	s_nop 1
	v_cndmask_b32_e32 v64, 2.0, v133, vcc
	v_cmp_neq_f32_e32 vcc, 0, v65
	s_nop 1
	v_cndmask_b32_e32 v65, 2.0, v134, vcc
	v_cmp_neq_f32_e32 vcc, 0, v156
	s_nop 1
	v_cndmask_b32_e32 v133, 2.0, v158, vcc

.LBB0_291:
	s_waitcnt vmcnt(0)
	s_mov_b64 s[100:101], exec
	s_mov_b64 exec, s[12:13]
	global_load_dword v184, v[174:175], off sc1
	s_mov_b64 exec, s[42:43]
	global_atomic_add v221, v[182:183], v181, off sc0
	s_mov_b64 exec, s[100:101]
	s_mov_b64 s[44:45], 0

.LBB0_342:
	s_waitcnt vmcnt(0)
	s_mov_b64 s[100:101], exec
	s_mov_b64 exec, s[12:13]
	global_load_dword v184, v[174:175], off sc1
	s_mov_b64 exec, s[42:43]
	global_atomic_add v221, v[182:183], v181, off sc0
	s_mov_b64 exec, s[100:101]
	s_mov_b64 s[28:29], 0
